# v31: GEMM3a epilogue: both halves' sigmoid(g_b) tile loads issued up front into free fragment registers (one exposed round trip instead of two), counted waits shifted by the eight stores
# speedup vs baseline: 1.0034x; 1.0008x over previous
; __device__ __forceinline__ float bflo(unsigned w) { return __uint_as_float(w << 16); }
; __device__ __forceinline__ float bfhi(unsigned w) { return __uint_as_float(w & 0xffff0000u); }
; __device__ __forceinline__ unsigned cvt_pk_bf16(float lo, float hi) { unsigned r; asm volatile("v_cvt_pk_bf16_f32 %0, %1, %2" : "=v"(r) : "v"(lo), "v"(hi)); return r; }
;     __device__ __forceinline__ void operator()(const f32x4 (&acc)[2][2][4][2], const pg8::Unit& u, int wr, int wc, int fr, int fq) const {
;         const int row0 = u.pm * 256 + wr * 64 + fr, col0 = u.pn * 256 + wc * 32 + 8 * fq;
;         unsigned boff = (unsigned)row0 * 2048u + (unsigned)col0 * 2u; asm volatile("" : "+v"(boff));
; #pragma unroll
;         for (int ai = 0; ai < 2; ++ai) {
;             u32x4 gb[4][2];
; #pragma unroll
;             for (int m = 0; m < 4; ++m) { const bf16_t* rowp = (const bf16_t*)((const char*)PJ + (size_t)(boff + (unsigned)((ai * 128 + m * 16) * 2048)));
; #pragma unroll
;                 for (int bj = 0; bj < 2; ++bj) gb[m][bj] = *(const u32x4*)(rowp + T_GB + bj * 128); }
;             __builtin_amdgcn_sched_barrier(0);
; #pragma unroll
;             for (int m = 0; m < 4; ++m) { bf16_t* rowp = (bf16_t*)((char*)PJ + (size_t)(boff + (unsigned)((ai * 128 + m * 16) * 2048)));
; #pragma unroll
;                 for (int bj = 0; bj < 2; ++bj) {
;                     const u32x4 b = gb[m][bj];
;                     const f32x4 v0 = acc[ai][bj][m][0] * (f32x4){bflo(b.x), bfhi(b.x), bflo(b.y), bfhi(b.y)}, v1 = acc[ai][bj][m][1] * (f32x4){bflo(b.z), bfhi(b.z), bflo(b.w), bfhi(b.w)};
;                     u32x4 w; w.x = cvt_pk_bf16(v0[0], v0[1]); w.y = cvt_pk_bf16(v0[2], v0[3]); w.z = cvt_pk_bf16(v1[0], v1[1]); w.w = cvt_pk_bf16(v1[2], v1[3]);
;                     *(u32x4*)(rowp + T_GV + bj * 128) = w;
;                 } }
;             asm volatile("" ::: "memory");
;         }
;     }
.LBB0_790:
	v_mov_b32_e32 v189, v1
	s_nop 0
	v_lshl_add_u64 v[164:165], s[44:45], 0, v[188:189]
	v_add_co_u32_e32 v2, vcc, 0x18000000, v164
	v_add_u32_e32 v0, 0x8000, v188
	s_nop 0
	v_addc_co_u32_e32 v3, vcc, 0, v165, vcc
	v_lshl_add_u64 v[166:167], s[44:45], 0, v[0:1]
	global_load_dwordx4 v[140:143], v[2:3], off
	global_load_dwordx4 v[144:147], v[2:3], off offset:256
	v_add_co_u32_e32 v2, vcc, 0x18000000, v166
	v_add_u32_e32 v0, 0x10000, v188
	s_nop 0
	v_addc_co_u32_e32 v3, vcc, 0, v167, vcc
	v_lshl_add_u64 v[168:169], s[44:45], 0, v[0:1]
	global_load_dwordx4 v[148:151], v[2:3], off
	global_load_dwordx4 v[152:155], v[2:3], off offset:256
	v_add_co_u32_e32 v2, vcc, 0x18000000, v168
	v_add_u32_e32 v0, 0x18000, v188
	s_nop 0
	v_addc_co_u32_e32 v3, vcc, 0, v169, vcc
	global_load_dwordx4 v[156:159], v[2:3], off
	global_load_dwordx4 v[160:163], v[2:3], off offset:256
	v_lshl_add_u64 v[2:3], s[44:45], 0, v[0:1]
	v_add_co_u32_e32 v132, vcc, 0x18000000, v2
	s_nop 1
	v_addc_co_u32_e32 v133, vcc, 0, v3, vcc
	global_load_dwordx4 v[136:139], v[132:133], off
	s_nop 0
	global_load_dwordx4 v[132:135], v[132:133], off offset:256
	v_add_u32_e32 v252, 0x40000, v188
	v_mov_b32_e32 v253, v1
	v_lshl_add_u64 v[252:253], s[44:45], 0, v[252:253]
	v_add_co_u32_e32 v252, vcc, 0x18000000, v252
	s_nop 1
	v_addc_co_u32_e32 v253, vcc, 0, v253, vcc
	global_load_dwordx4 v[200:203], v[252:253], off
	global_load_dwordx4 v[204:207], v[252:253], off offset:256
	v_add_u32_e32 v252, 0x48000, v188
	v_mov_b32_e32 v253, v1
	v_lshl_add_u64 v[252:253], s[44:45], 0, v[252:253]
	v_add_co_u32_e32 v252, vcc, 0x18000000, v252
	s_nop 1
	v_addc_co_u32_e32 v253, vcc, 0, v253, vcc
	global_load_dwordx4 v[208:211], v[252:253], off
	global_load_dwordx4 v[212:215], v[252:253], off offset:256
	v_add_u32_e32 v252, 0x50000, v188
	v_mov_b32_e32 v253, v1
	v_lshl_add_u64 v[252:253], s[44:45], 0, v[252:253]
	v_add_co_u32_e32 v252, vcc, 0x18000000, v252
	s_nop 1
	v_addc_co_u32_e32 v253, vcc, 0, v253, vcc
	global_load_dwordx4 v[216:219], v[252:253], off
	global_load_dwordx4 v[240:243], v[252:253], off offset:256
	v_add_u32_e32 v252, 0x58000, v188
	v_mov_b32_e32 v253, v1
	v_lshl_add_u64 v[252:253], s[44:45], 0, v[252:253]
	v_add_co_u32_e32 v252, vcc, 0x18000000, v252
	s_nop 1
	v_addc_co_u32_e32 v253, vcc, 0, v253, vcc
	global_load_dwordx4 v[244:247], v[252:253], off
	global_load_dwordx4 v[248:251], v[252:253], off offset:256
	s_waitcnt vmcnt(8)
	v_lshlrev_b32_e32 v170, 16, v140
	v_and_b32_e32 v171, 0xffff0000, v140
	v_lshlrev_b32_e32 v140, 16, v141
	v_and_b32_e32 v141, 0xffff0000, v141
	v_pk_mul_f32 v[130:131], v[130:131], v[140:141]
	v_pk_mul_f32 v[128:129], v[128:129], v[170:171]
	v_lshlrev_b32_e32 v140, 16, v142
	v_and_b32_e32 v141, 0xffff0000, v142
	v_lshlrev_b32_e32 v142, 16, v143
	v_and_b32_e32 v143, 0xffff0000, v143
	v_pk_mul_f32 v[142:143], v[126:127], v[142:143]
	v_pk_mul_f32 v[126:127], v[124:125], v[140:141]
	v_cvt_pk_bf16_f32 v124, v128, v129
	v_add_co_u32_e32 v128, vcc, s73, v164
	v_cvt_pk_bf16_f32 v125, v130, v131
	v_cvt_pk_bf16_f32 v126, v126, v127
	v_cvt_pk_bf16_f32 v127, v142, v143
	v_add_u32_e32 v0, 0x40000, v188
	s_nop 0
	v_addc_co_u32_e32 v129, vcc, 0, v165, vcc
	global_store_dwordx4 v[128:129], v[124:127], off
	s_nop 1
	v_lshlrev_b32_e32 v124, 16, v144
	v_and_b32_e32 v125, 0xffff0000, v144
	v_lshlrev_b32_e32 v126, 16, v145
	v_and_b32_e32 v127, 0xffff0000, v145
	v_pk_mul_f32 v[122:123], v[122:123], v[126:127]
	v_pk_mul_f32 v[120:121], v[120:121], v[124:125]
	v_lshlrev_b32_e32 v124, 16, v146
	v_and_b32_e32 v125, 0xffff0000, v146
	v_lshlrev_b32_e32 v126, 16, v147
	v_and_b32_e32 v127, 0xffff0000, v147
	v_pk_mul_f32 v[126:127], v[118:119], v[126:127]
	v_pk_mul_f32 v[118:119], v[116:117], v[124:125]
	v_cvt_pk_bf16_f32 v116, v120, v121
	v_cvt_pk_bf16_f32 v117, v122, v123
	s_nop 0
	v_cvt_pk_bf16_f32 v118, v118, v119
	v_cvt_pk_bf16_f32 v119, v126, v127
	global_store_dwordx4 v[128:129], v[116:119], off offset:256
	s_nop 1
	v_lshlrev_b32_e32 v116, 16, v148
	v_and_b32_e32 v117, 0xffff0000, v148
	v_lshlrev_b32_e32 v118, 16, v149
	v_and_b32_e32 v119, 0xffff0000, v149
	v_pk_mul_f32 v[114:115], v[114:115], v[118:119]
	v_pk_mul_f32 v[112:113], v[112:113], v[116:117]
	v_lshlrev_b32_e32 v116, 16, v150
	v_and_b32_e32 v117, 0xffff0000, v150
	v_lshlrev_b32_e32 v118, 16, v151
	v_and_b32_e32 v119, 0xffff0000, v151
	v_pk_mul_f32 v[118:119], v[110:111], v[118:119]
	v_pk_mul_f32 v[110:111], v[108:109], v[116:117]
	v_cvt_pk_bf16_f32 v108, v112, v113
	v_add_co_u32_e32 v112, vcc, s73, v166
	v_cvt_pk_bf16_f32 v109, v114, v115
	v_cvt_pk_bf16_f32 v110, v110, v111
	v_cvt_pk_bf16_f32 v111, v118, v119
	s_nop 1
	v_addc_co_u32_e32 v113, vcc, 0, v167, vcc
	global_store_dwordx4 v[112:113], v[108:111], off
	s_nop 1
	v_lshlrev_b32_e32 v108, 16, v152
	v_and_b32_e32 v109, 0xffff0000, v152
	v_lshlrev_b32_e32 v110, 16, v153
	v_and_b32_e32 v111, 0xffff0000, v153
	v_pk_mul_f32 v[106:107], v[106:107], v[110:111]
	v_pk_mul_f32 v[104:105], v[104:105], v[108:109]
	v_lshlrev_b32_e32 v108, 16, v154
	v_and_b32_e32 v109, 0xffff0000, v154
	v_lshlrev_b32_e32 v110, 16, v155
	v_and_b32_e32 v111, 0xffff0000, v155
	v_pk_mul_f32 v[110:111], v[102:103], v[110:111]
	v_pk_mul_f32 v[102:103], v[100:101], v[108:109]
	v_cvt_pk_bf16_f32 v100, v104, v105
	v_cvt_pk_bf16_f32 v101, v106, v107
	s_nop 0
	v_cvt_pk_bf16_f32 v102, v102, v103
	v_cvt_pk_bf16_f32 v103, v110, v111
	global_store_dwordx4 v[112:113], v[100:103], off offset:256
	s_nop 1
	v_lshlrev_b32_e32 v100, 16, v156
	v_and_b32_e32 v101, 0xffff0000, v156
	v_lshlrev_b32_e32 v102, 16, v157
	v_and_b32_e32 v103, 0xffff0000, v157
	v_pk_mul_f32 v[98:99], v[98:99], v[102:103]
	v_pk_mul_f32 v[96:97], v[96:97], v[100:101]
; __device__ __forceinline__ float bflo(unsigned w) { return __uint_as_float(w << 16); }
; __device__ __forceinline__ float bfhi(unsigned w) { return __uint_as_float(w & 0xffff0000u); }
; __device__ __forceinline__ unsigned cvt_pk_bf16(float lo, float hi) { unsigned r; asm volatile("v_cvt_pk_bf16_f32 %0, %1, %2" : "=v"(r) : "v"(lo), "v"(hi)); return r; }
;     __device__ __forceinline__ void operator()(const f32x4 (&acc)[2][2][4][2], const pg8::Unit& u, int wr, int wc, int fr, int fq) const {
;         const int row0 = u.pm * 256 + wr * 64 + fr, col0 = u.pn * 256 + wc * 32 + 8 * fq;
;         unsigned boff = (unsigned)row0 * 2048u + (unsigned)col0 * 2u; asm volatile("" : "+v"(boff));
; #pragma unroll
;         for (int ai = 0; ai < 2; ++ai) {
;             u32x4 gb[4][2];
; #pragma unroll
;             for (int m = 0; m < 4; ++m) { const bf16_t* rowp = (const bf16_t*)((const char*)PJ + (size_t)(boff + (unsigned)((ai * 128 + m * 16) * 2048)));
; #pragma unroll
;                 for (int bj = 0; bj < 2; ++bj) gb[m][bj] = *(const u32x4*)(rowp + T_GB + bj * 128); }
;             __builtin_amdgcn_sched_barrier(0);
; #pragma unroll
;             for (int m = 0; m < 4; ++m) { bf16_t* rowp = (bf16_t*)((char*)PJ + (size_t)(boff + (unsigned)((ai * 128 + m * 16) * 2048)));
; #pragma unroll
;                 for (int bj = 0; bj < 2; ++bj) {
;                     const u32x4 b = gb[m][bj];
;                     const f32x4 v0 = acc[ai][bj][m][0] * (f32x4){bflo(b.x), bfhi(b.x), bflo(b.y), bfhi(b.y)}, v1 = acc[ai][bj][m][1] * (f32x4){bflo(b.z), bfhi(b.z), bflo(b.w), bfhi(b.w)};
;                     u32x4 w; w.x = cvt_pk_bf16(v0[0], v0[1]); w.y = cvt_pk_bf16(v0[2], v0[3]); w.z = cvt_pk_bf16(v1[0], v1[1]); w.w = cvt_pk_bf16(v1[2], v1[3]);
;                     *(u32x4*)(rowp + T_GV + bj * 128) = w;
;                 } }
;             asm volatile("" ::: "memory");
;         }
;     }
	v_lshlrev_b32_e32 v100, 16, v158
	v_and_b32_e32 v101, 0xffff0000, v158
	v_lshlrev_b32_e32 v102, 16, v159
	v_and_b32_e32 v103, 0xffff0000, v159
	v_pk_mul_f32 v[102:103], v[94:95], v[102:103]
	v_pk_mul_f32 v[94:95], v[92:93], v[100:101]
	v_cvt_pk_bf16_f32 v92, v96, v97
	v_add_co_u32_e32 v96, vcc, s73, v168
	v_cvt_pk_bf16_f32 v93, v98, v99
	v_cvt_pk_bf16_f32 v94, v94, v95
	v_cvt_pk_bf16_f32 v95, v102, v103
	v_lshl_add_u64 v[100:101], s[44:45], 0, v[0:1]
	s_nop 0
	v_addc_co_u32_e32 v97, vcc, 0, v169, vcc
	global_store_dwordx4 v[96:97], v[92:95], off
	v_add_co_u32_e32 v2, vcc, s73, v2
	s_nop 0
	v_lshlrev_b32_e32 v92, 16, v160
	v_and_b32_e32 v93, 0xffff0000, v160
	v_lshlrev_b32_e32 v94, 16, v161
	v_and_b32_e32 v95, 0xffff0000, v161
	v_pk_mul_f32 v[90:91], v[90:91], v[94:95]
	v_pk_mul_f32 v[88:89], v[88:89], v[92:93]
	v_lshlrev_b32_e32 v92, 16, v162
	v_and_b32_e32 v93, 0xffff0000, v162
	v_lshlrev_b32_e32 v94, 16, v163
	v_and_b32_e32 v95, 0xffff0000, v163
	v_pk_mul_f32 v[94:95], v[86:87], v[94:95]
	v_pk_mul_f32 v[86:87], v[84:85], v[92:93]
	v_cvt_pk_bf16_f32 v84, v88, v89
	v_cvt_pk_bf16_f32 v85, v90, v91
	v_addc_co_u32_e32 v3, vcc, 0, v3, vcc
	v_cvt_pk_bf16_f32 v86, v86, v87
	v_cvt_pk_bf16_f32 v87, v94, v95
	global_store_dwordx4 v[96:97], v[84:87], off offset:256
	v_add_u32_e32 v0, 0x48000, v188
	v_lshl_add_u64 v[102:103], s[44:45], 0, v[0:1]
	v_lshlrev_b32_e32 v84, 16, v136
	v_and_b32_e32 v85, 0xffff0000, v136
	v_lshlrev_b32_e32 v86, 16, v137
	v_and_b32_e32 v87, 0xffff0000, v137
	v_pk_mul_f32 v[82:83], v[82:83], v[86:87]
	v_pk_mul_f32 v[80:81], v[80:81], v[84:85]
	v_lshlrev_b32_e32 v84, 16, v138
	v_and_b32_e32 v85, 0xffff0000, v138
	v_lshlrev_b32_e32 v86, 16, v139
	v_and_b32_e32 v87, 0xffff0000, v139
	v_pk_mul_f32 v[86:87], v[78:79], v[86:87]
	v_pk_mul_f32 v[78:79], v[76:77], v[84:85]
	v_cvt_pk_bf16_f32 v76, v80, v81
	v_cvt_pk_bf16_f32 v77, v82, v83
	v_add_u32_e32 v0, 0x50000, v188
	v_cvt_pk_bf16_f32 v78, v78, v79
	v_cvt_pk_bf16_f32 v79, v86, v87
	global_store_dwordx4 v[2:3], v[76:79], off
	v_lshl_add_u64 v[104:105], s[44:45], 0, v[0:1]
	v_add_u32_e32 v0, 0x58000, v188
	v_lshlrev_b32_e32 v76, 16, v132
	v_and_b32_e32 v77, 0xffff0000, v132
	v_lshlrev_b32_e32 v78, 16, v133
	v_and_b32_e32 v79, 0xffff0000, v133
	v_pk_mul_f32 v[74:75], v[74:75], v[78:79]
	v_pk_mul_f32 v[72:73], v[72:73], v[76:77]
	v_lshlrev_b32_e32 v76, 16, v134
	v_and_b32_e32 v77, 0xffff0000, v134
	v_lshlrev_b32_e32 v78, 16, v135
	v_and_b32_e32 v79, 0xffff0000, v135
	v_pk_mul_f32 v[78:79], v[70:71], v[78:79]
	v_pk_mul_f32 v[70:71], v[68:69], v[76:77]
	v_cvt_pk_bf16_f32 v68, v72, v73
	v_cvt_pk_bf16_f32 v69, v74, v75
	s_nop 0
	v_cvt_pk_bf16_f32 v70, v70, v71
	v_cvt_pk_bf16_f32 v71, v78, v79
	global_store_dwordx4 v[2:3], v[68:71], off offset:256
	v_add_co_u32_e32 v2, vcc, s72, v100
	s_nop 1
	v_addc_co_u32_e32 v3, vcc, 0, v101, vcc
	v_add_co_u32_e32 v2, vcc, s72, v102
	s_nop 1
	v_addc_co_u32_e32 v3, vcc, 0, v103, vcc
	v_add_co_u32_e32 v2, vcc, s72, v104
	s_nop 1
	v_addc_co_u32_e32 v3, vcc, 0, v105, vcc
	v_lshl_add_u64 v[2:3], s[44:45], 0, v[0:1]
	v_add_co_u32_e32 v68, vcc, s72, v2
	s_nop 1
	v_addc_co_u32_e32 v69, vcc, 0, v3, vcc
	s_nop 0
	s_waitcnt vmcnt(15)
	v_lshlrev_b32_e32 v106, 16, v200
	v_and_b32_e32 v107, 0xffff0000, v200
	v_lshlrev_b32_e32 v76, 16, v201
	v_and_b32_e32 v77, 0xffff0000, v201
	v_pk_mul_f32 v[66:67], v[66:67], v[76:77]
	v_pk_mul_f32 v[64:65], v[64:65], v[106:107]
	v_lshlrev_b32_e32 v76, 16, v202
	v_and_b32_e32 v77, 0xffff0000, v202
	v_lshlrev_b32_e32 v78, 16, v203
	v_and_b32_e32 v79, 0xffff0000, v203
	v_pk_mul_f32 v[78:79], v[62:63], v[78:79]
	v_pk_mul_f32 v[62:63], v[60:61], v[76:77]
	v_cvt_pk_bf16_f32 v60, v64, v65
	v_add_co_u32_e32 v64, vcc, s73, v100
	v_cvt_pk_bf16_f32 v61, v66, v67
	v_cvt_pk_bf16_f32 v62, v62, v63
	v_cvt_pk_bf16_f32 v63, v78, v79
	s_nop 1
	v_addc_co_u32_e32 v65, vcc, 0, v101, vcc
	global_store_dwordx4 v[64:65], v[60:63], off
	s_waitcnt vmcnt(15)
	s_nop 0
	v_lshlrev_b32_e32 v60, 16, v204
	v_and_b32_e32 v61, 0xffff0000, v204
	v_lshlrev_b32_e32 v62, 16, v205
	v_and_b32_e32 v63, 0xffff0000, v205
	v_pk_mul_f32 v[58:59], v[58:59], v[62:63]
	v_pk_mul_f32 v[56:57], v[56:57], v[60:61]
	v_lshlrev_b32_e32 v60, 16, v206
	v_and_b32_e32 v61, 0xffff0000, v206
	v_lshlrev_b32_e32 v62, 16, v207
	v_and_b32_e32 v63, 0xffff0000, v207
	v_pk_mul_f32 v[62:63], v[54:55], v[62:63]
	v_pk_mul_f32 v[54:55], v[52:53], v[60:61]
	v_cvt_pk_bf16_f32 v52, v56, v57
	v_cvt_pk_bf16_f32 v53, v58, v59
	s_nop 0
	v_cvt_pk_bf16_f32 v54, v54, v55
	v_cvt_pk_bf16_f32 v55, v62, v63
	global_store_dwordx4 v[64:65], v[52:55], off offset:256
	s_waitcnt vmcnt(15)
; __device__ __forceinline__ float bflo(unsigned w) { return __uint_as_float(w << 16); }
; __device__ __forceinline__ float bfhi(unsigned w) { return __uint_as_float(w & 0xffff0000u); }
; __device__ __forceinline__ unsigned cvt_pk_bf16(float lo, float hi) { unsigned r; asm volatile("v_cvt_pk_bf16_f32 %0, %1, %2" : "=v"(r) : "v"(lo), "v"(hi)); return r; }
;     __device__ __forceinline__ void operator()(const f32x4 (&acc)[2][2][4][2], const pg8::Unit& u, int wr, int wc, int fr, int fq) const {
;     ...
;             for (int m = 0; m < 4; ++m) { const bf16_t* rowp = (const bf16_t*)((const char*)PJ + (size_t)(boff + (unsigned)((ai * 128 + m * 16) * 2048)));
; #pragma unroll
;                 for (int bj = 0; bj < 2; ++bj) gb[m][bj] = *(const u32x4*)(rowp + T_GB + bj * 128); }
;             __builtin_amdgcn_sched_barrier(0);
; #pragma unroll
;             for (int m = 0; m < 4; ++m) { bf16_t* rowp = (bf16_t*)((char*)PJ + (size_t)(boff + (unsigned)((ai * 128 + m * 16) * 2048)));
; #pragma unroll
;                 for (int bj = 0; bj < 2; ++bj) {
;                     const u32x4 b = gb[m][bj];
;                     const f32x4 v0 = acc[ai][bj][m][0] * (f32x4){bflo(b.x), bfhi(b.x), bflo(b.y), bfhi(b.y)}, v1 = acc[ai][bj][m][1] * (f32x4){bflo(b.z), bfhi(b.z), bflo(b.w), bfhi(b.w)};
;                     u32x4 w; w.x = cvt_pk_bf16(v0[0], v0[1]); w.y = cvt_pk_bf16(v0[2], v0[3]); w.z = cvt_pk_bf16(v1[0], v1[1]); w.w = cvt_pk_bf16(v1[2], v1[3]);
;                     *(u32x4*)(rowp + T_GV + bj * 128) = w;
;                 } }
	s_nop 0
	v_lshlrev_b32_e32 v52, 16, v208
	v_and_b32_e32 v53, 0xffff0000, v208
	v_lshlrev_b32_e32 v54, 16, v209
	v_and_b32_e32 v55, 0xffff0000, v209
	v_pk_mul_f32 v[50:51], v[50:51], v[54:55]
	v_pk_mul_f32 v[48:49], v[48:49], v[52:53]
	v_lshlrev_b32_e32 v52, 16, v210
	v_and_b32_e32 v53, 0xffff0000, v210
	v_lshlrev_b32_e32 v54, 16, v211
	v_and_b32_e32 v55, 0xffff0000, v211
	v_pk_mul_f32 v[54:55], v[46:47], v[54:55]
	v_pk_mul_f32 v[46:47], v[44:45], v[52:53]
	v_cvt_pk_bf16_f32 v44, v48, v49
	v_add_co_u32_e32 v48, vcc, s73, v102
	v_cvt_pk_bf16_f32 v45, v50, v51
	v_cvt_pk_bf16_f32 v46, v46, v47
	v_cvt_pk_bf16_f32 v47, v54, v55
	s_nop 1
	v_addc_co_u32_e32 v49, vcc, 0, v103, vcc
	global_store_dwordx4 v[48:49], v[44:47], off
	s_waitcnt vmcnt(15)
	s_nop 0
	v_lshlrev_b32_e32 v44, 16, v212
	v_and_b32_e32 v45, 0xffff0000, v212
	v_lshlrev_b32_e32 v46, 16, v213
	v_and_b32_e32 v47, 0xffff0000, v213
	v_pk_mul_f32 v[42:43], v[42:43], v[46:47]
	v_pk_mul_f32 v[40:41], v[40:41], v[44:45]
	v_lshlrev_b32_e32 v44, 16, v214
	v_and_b32_e32 v45, 0xffff0000, v214
	v_lshlrev_b32_e32 v46, 16, v215
	v_and_b32_e32 v47, 0xffff0000, v215
	v_pk_mul_f32 v[46:47], v[38:39], v[46:47]
	v_pk_mul_f32 v[38:39], v[36:37], v[44:45]
	v_cvt_pk_bf16_f32 v36, v40, v41
	v_cvt_pk_bf16_f32 v37, v42, v43
	s_nop 0
	v_cvt_pk_bf16_f32 v38, v38, v39
	v_cvt_pk_bf16_f32 v39, v46, v47
	global_store_dwordx4 v[48:49], v[36:39], off offset:256
	s_waitcnt vmcnt(15)
	s_nop 0
	v_lshlrev_b32_e32 v36, 16, v216
	v_and_b32_e32 v37, 0xffff0000, v216
	v_lshlrev_b32_e32 v38, 16, v217
	v_and_b32_e32 v39, 0xffff0000, v217
	v_pk_mul_f32 v[34:35], v[34:35], v[38:39]
	v_pk_mul_f32 v[32:33], v[32:33], v[36:37]
	v_lshlrev_b32_e32 v36, 16, v218
	v_and_b32_e32 v37, 0xffff0000, v218
	v_lshlrev_b32_e32 v38, 16, v219
	v_and_b32_e32 v39, 0xffff0000, v219
	v_pk_mul_f32 v[38:39], v[30:31], v[38:39]
	v_pk_mul_f32 v[30:31], v[28:29], v[36:37]
	v_cvt_pk_bf16_f32 v28, v32, v33
	v_add_co_u32_e32 v32, vcc, s73, v104
	v_cvt_pk_bf16_f32 v29, v34, v35
	v_cvt_pk_bf16_f32 v30, v30, v31
	v_cvt_pk_bf16_f32 v31, v38, v39
	s_nop 1
	v_addc_co_u32_e32 v33, vcc, 0, v105, vcc
	global_store_dwordx4 v[32:33], v[28:31], off
	s_waitcnt vmcnt(15)
	s_nop 0
	v_lshlrev_b32_e32 v28, 16, v240
	v_and_b32_e32 v29, 0xffff0000, v240
	v_lshlrev_b32_e32 v30, 16, v241
	v_and_b32_e32 v31, 0xffff0000, v241
	v_pk_mul_f32 v[26:27], v[26:27], v[30:31]
	v_pk_mul_f32 v[24:25], v[24:25], v[28:29]
	v_lshlrev_b32_e32 v28, 16, v242
	v_and_b32_e32 v29, 0xffff0000, v242
	v_lshlrev_b32_e32 v30, 16, v243
	v_and_b32_e32 v31, 0xffff0000, v243
	v_pk_mul_f32 v[30:31], v[22:23], v[30:31]
	v_pk_mul_f32 v[22:23], v[20:21], v[28:29]
	v_cvt_pk_bf16_f32 v20, v24, v25
	v_cvt_pk_bf16_f32 v21, v26, v27
	s_nop 0
	v_cvt_pk_bf16_f32 v22, v22, v23
	v_cvt_pk_bf16_f32 v23, v30, v31
	global_store_dwordx4 v[32:33], v[20:23], off offset:256
	s_waitcnt vmcnt(15)
	s_nop 0
	v_lshlrev_b32_e32 v20, 16, v244
	v_and_b32_e32 v21, 0xffff0000, v244
	v_lshlrev_b32_e32 v22, 16, v245
	v_and_b32_e32 v23, 0xffff0000, v245
	v_pk_mul_f32 v[18:19], v[18:19], v[22:23]
	v_pk_mul_f32 v[16:17], v[16:17], v[20:21]
	v_lshlrev_b32_e32 v20, 16, v246
	v_and_b32_e32 v21, 0xffff0000, v246
	v_lshlrev_b32_e32 v22, 16, v247
	v_and_b32_e32 v23, 0xffff0000, v247
	v_pk_mul_f32 v[22:23], v[14:15], v[22:23]
	v_pk_mul_f32 v[14:15], v[12:13], v[20:21]
	v_cvt_pk_bf16_f32 v12, v16, v17
	v_add_co_u32_e32 v16, vcc, s73, v2
	v_cvt_pk_bf16_f32 v13, v18, v19
	s_waitcnt vmcnt(14)
	v_lshlrev_b32_e32 v2, 16, v248
	v_addc_co_u32_e32 v17, vcc, 0, v3, vcc
	v_and_b32_e32 v3, 0xffff0000, v248
	v_cvt_pk_bf16_f32 v14, v14, v15
	v_cvt_pk_bf16_f32 v15, v22, v23
	global_store_dwordx4 v[16:17], v[12:15], off
	v_pk_mul_f32 v[2:3], v[8:9], v[2:3]
	v_lshlrev_b32_e32 v8, 16, v250
	v_lshlrev_b32_e32 v12, 16, v249
	v_and_b32_e32 v13, 0xffff0000, v249
	v_and_b32_e32 v9, 0xffff0000, v250
	v_pk_mul_f32 v[10:11], v[10:11], v[12:13]
	v_lshlrev_b32_e32 v12, 16, v251
	v_and_b32_e32 v13, 0xffff0000, v251
	v_pk_mul_f32 v[4:5], v[4:5], v[8:9]
	v_pk_mul_f32 v[6:7], v[6:7], v[12:13]
	v_cvt_pk_bf16_f32 v2, v2, v3
	v_cvt_pk_bf16_f32 v3, v10, v11
	v_cvt_pk_bf16_f32 v4, v4, v5
	s_andn2_b64 vcc, exec, s[4:5]
	v_cvt_pk_bf16_f32 v5, v6, v7
	global_store_dwordx4 v[16:17], v[2:5], off offset:256
	s_mov_b64 s[4:5], -1
	s_cbranch_vccnz .LBB0_775
	s_andn2_b64 vcc, exec, s[10:11]
	s_cbranch_vccnz .LBB0_774
	s_barrier
	s_branch .LBB0_774
